# rank-based P6-end window with steeper profile 7/6/5/4/4/3/2/1
# baseline (speedup 1.0000x reference)
; __global__ void __launch_bounds__(NTHREADS, 2) mk_fwd(Params P) {
;     ...
;     if (IN(7)) {
;         transpose_convert(lds, P.w_out + (size_t)2048 * 2048, WOUT1, 2048, 2048, G, bid);
;         transpose_convert(lds, P.w_gate + (size_t)2048 * 2048, WG1, 2048, 2048, G, bid);
;     }
.Ldyn7_nofetch:
	s_or_b64 exec, exec, s[18:19]
	s_waitcnt lgkmcnt(0)
	s_barrier
	ds_read_b32 v1, v46
	s_waitcnt lgkmcnt(0)
	v_readfirstlane_b32 s99, v1
	s_and_b32 s99, s99, 0xff
	s_and_b32 s101, s99, 1
	s_lshr_b32 s99, s99, 1
	s_lshr_b32 s4, s99, 4
	s_and_b32 s5, s99, 15
	s_mov_b32 s100, 7
	s_mov_b32 s99, 0
	s_cmp_lt_u32 s4, 1
	s_cbranch_scc1 .Lrk7_done
	s_mov_b32 s100, 6
	s_movk_i32 s99, 112
	s_cmp_lt_u32 s4, 2
	s_cbranch_scc1 .Lrk7_done
	s_mov_b32 s100, 5
	s_movk_i32 s99, 208
	s_cmp_lt_u32 s4, 3
	s_cbranch_scc1 .Lrk7_done
	s_mov_b32 s100, 4
	s_movk_i32 s99, 288
	s_cmp_lt_u32 s4, 4
	s_cbranch_scc1 .Lrk7_done
	s_mov_b32 s100, 4
	s_movk_i32 s99, 352
	s_cmp_lt_u32 s4, 5
	s_cbranch_scc1 .Lrk7_done
	s_mov_b32 s100, 3
	s_movk_i32 s99, 416
	s_cmp_lt_u32 s4, 6
	s_cbranch_scc1 .Lrk7_done
	s_mov_b32 s100, 2
	s_movk_i32 s99, 464
	s_cmp_lt_u32 s4, 7
	s_cbranch_scc1 .Lrk7_done
	s_mov_b32 s100, 1
	s_movk_i32 s99, 496
